# P0: idle workgroups also pre-touch the x rows their waves normalise first in P1 (memory-side cache warming while HBM is idle)
# baseline (speedup 1.0000x reference)
.Lwarm0:
	s_cmpk_lg_i32 s82, 0x100
	s_cbranch_scc1 .LBB0_36
	s_and_b32 s1, s0, 7
	s_sub_i32 s6, s0, 48
	s_lshr_b32 s6, s6, 3
	s_lshl_b32 s6, s6, 9
	v_add_u32_e32 v0, s6, v193
	s_waitcnt lgkmcnt(0)
	v_lshrrev_b32_e32 v1, 12, v0
	v_bfe_u32 v2, v0, 2, 10
	v_and_b32_e32 v3, 3, v0
	v_mul_u32_u24_e32 v4, 0x6000, v2
	v_lshl_add_u32 v5, v1, 3, s1
	v_lshl_add_u32 v4, v5, 9, v4
	v_lshl_add_u32 v4, v3, 7, v4
	global_load_dword v6, v4, s[68:69]
	v_add_u32_e32 v0, 0x3400, v0
	s_movk_i32 s6, 0x6000
	v_cmp_gt_u32_e32 vcc, s6, v0
	s_and_saveexec_b64 s[6:7], vcc
	v_lshrrev_b32_e32 v1, 12, v0
	v_bfe_u32 v2, v0, 2, 10
	v_and_b32_e32 v3, 3, v0
	v_mul_u32_u24_e32 v4, 0x6000, v2
	v_lshl_add_u32 v5, v1, 3, s1
	v_lshl_add_u32 v4, v5, 9, v4
	v_lshl_add_u32 v4, v3, 7, v4
	global_load_dword v7, v4, s[68:69]
	s_or_b64 exec, exec, s[6:7]
	v_lshrrev_b32_e32 v0, 6, v193
	v_readlane_b32 s6, v254, 4
	s_lshl_b32 s6, s6, 3
	v_add_u32_e32 v0, s6, v0
	v_bfe_u32 v1, v193, 5, 1
	v_lshl_add_u32 v0, v1, 11, v0
	v_and_b32_e32 v1, 31, v193
	v_lshlrev_b32_e32 v1, 7, v1
	v_lshl_add_u32 v1, v0, 12, v1
	global_load_dword v6, v1, s[60:61]
	v_add_u32_e32 v1, 0x1000000, v1
	global_load_dword v7, v1, s[60:61]
	s_waitcnt vmcnt(0)
	s_branch .LBB0_36
